# attention item epilogue: the 16 gate loads issued up front with counted waits instead of one round trip per 8 bytes
# speedup vs baseline: 1.0139x; 1.0025x over previous
; DI size_t pix(int row, int col) { return ((size_t)(col >> 8) * MROWS + (size_t)row) * 256 + (size_t)(col & 255); }
; DI float bflo(unsigned w) { return __uint_as_float(w << 16); }
; DI float bfhi(unsigned w) { return __uint_as_float(w & 0xffff0000u); }
; DI unsigned cvt_pk_bf16(float lo, float hi) { unsigned r; asm volatile("v_cvt_pk_bf16_f32 %0, %1, %2" : "=v"(r) : "v"(lo), "v"(hi)); return r; }
; DI float siluf_(float v) { return v * __builtin_amdgcn_rcpf(1.0f + __expf(-v)); }
; DI void attn_item(const Params& p, int it, unsigned char* lds) {
;     ...
;     {
;         const float inv = 1.0f / (l_part + xchg32(l_part));
;         const size_t zo = pix(qrow, C_Z + h * 128); const size_t yo = (size_t)qrow * 2048 + h * 128;
; #pragma unroll
;         for (int c = 0; c < 4; ++c)
; #pragma unroll
;             for (int i4 = 0; i4 < 4; ++i4) { const int dv = 32 * c + 8 * i4 + 4 * hh;
;                 const u32x2 zz = *(const u32x2*)(P + zo + dv);
;                 const float o0 = oa[c][4 * i4 + 0] * inv * siluf_(bflo(zz.x)), o1 = oa[c][4 * i4 + 1] * inv * siluf_(bfhi(zz.x));
;                 const float o2 = oa[c][4 * i4 + 2] * inv * siluf_(bflo(zz.y)), o3 = oa[c][4 * i4 + 3] * inv * siluf_(bfhi(zz.y));
;                 u32x2 wv; wv.x = cvt_pk_bf16(o0, o1); wv.y = cvt_pk_bf16(o2, o3);
;                 *(u32x2*)(YA + yo + dv) = wv; }
.LBB0_555:
	s_add_i32 s12, s20, 0x63000
	v_lshl_add_u64 v[2:3], v[162:163], 0, s[12:13]
	v_lshlrev_b64 v[2:3], 9, v[2:3]
	v_lshl_add_u64 v[2:3], s[46:47], 0, v[2:3]
	s_lshl_b32 s12, s21, 1
	v_lshl_add_u64 v[2:3], v[2:3], 0, s[12:13]
	v_mov_b32_e32 v161, v1
	v_lshl_add_u64 v[4:5], v[2:3], 0, v[160:161]
	global_load_dwordx2 v[6:7], v[4:5], off
	global_load_dwordx2 v[82:83], v[4:5], off offset:16
	global_load_dwordx2 v[84:85], v[4:5], off offset:32
	global_load_dwordx2 v[86:87], v[4:5], off offset:48
	global_load_dwordx2 v[88:89], v[4:5], off offset:64
	global_load_dwordx2 v[90:91], v[4:5], off offset:80
	global_load_dwordx2 v[92:93], v[4:5], off offset:96
	global_load_dwordx2 v[94:95], v[4:5], off offset:112
	global_load_dwordx2 v[96:97], v[4:5], off offset:128
	global_load_dwordx2 v[98:99], v[4:5], off offset:144
	global_load_dwordx2 v[100:101], v[4:5], off offset:160
	global_load_dwordx2 v[102:103], v[4:5], off offset:176
	global_load_dwordx2 v[104:105], v[4:5], off offset:192
	global_load_dwordx2 v[106:107], v[4:5], off offset:208
	global_load_dwordx2 v[108:109], v[4:5], off offset:224
	global_load_dwordx2 v[110:111], v[4:5], off offset:240
	v_mov_b32_e32 v0, v218
	v_mov_b32_e32 v2, v218
	s_nop 1
	v_permlane32_swap_b32_e32 v0, v2
	v_cndmask_b32_e64 v0, v0, v2, s[4:5]
	v_add_f32_e32 v0, v218, v0
	v_div_scale_f32 v2, s[6:7], v0, v0, 1.0
	v_rcp_f32_e32 v10, v2
	v_div_scale_f32 v9, vcc, 1.0, v0, 1.0
	v_mov_b32_e32 v8, v64
	v_fma_f32 v3, -v2, v10, 1.0
	v_fmac_f32_e32 v10, v3, v10
	v_mul_f32_e32 v11, v9, v10
	v_fma_f32 v13, -v2, v11, v9
	v_fmac_f32_e32 v11, v13, v10
	v_fma_f32 v2, -v2, v11, v9
	v_div_fmas_f32 v2, v2, v10, v11
	v_div_fixup_f32 v2, v2, v0, 1.0
	v_mov_b32_e32 v10, v65
	v_mov_b32_e32 v14, v66
	s_lshl_b32 s6, s37, 1
	s_add_u32 s6, s28, s6
	s_addc_u32 s7, s29, 0
	v_mov_b32_e32 v64, v67
	s_add_i32 s19, s19, s78
	s_add_i32 s30, s30, s31
	s_cmpk_lt_i32 s19, 0x400
	s_waitcnt vmcnt(15)
	v_lshlrev_b32_e32 v3, 16, v6
	v_mul_f32_e32 v12, 0xbfb8aa3b, v3
	v_exp_f32_e32 v12, v12
	s_nop 0
	v_add_f32_e32 v9, 1.0, v12
	v_rcp_f32_e32 v9, v9
	v_lshlrev_b64 v[12:13], 12, v[162:163]
	v_pk_mul_f32 v[8:9], v[8:9], v[2:3]
	v_and_b32_e32 v3, 0xffff0000, v6
	v_mul_f32_e32 v0, 0xbfb8aa3b, v3
	v_exp_f32_e32 v0, v0
	v_mul_f32_e32 v8, v8, v9
	v_add_f32_e32 v0, 1.0, v0
	v_rcp_f32_e32 v11, v0
	s_nop 0
	v_pk_mul_f32 v[10:11], v[10:11], v[2:3]
	v_lshlrev_b32_e32 v3, 16, v7
	v_mul_f32_e32 v0, 0xbfb8aa3b, v3
	v_exp_f32_e32 v0, v0
	s_nop 0
	v_add_f32_e32 v0, 1.0, v0
	v_rcp_f32_e32 v15, v0
	s_nop 0
	v_pk_mul_f32 v[14:15], v[14:15], v[2:3]
	v_and_b32_e32 v3, 0xffff0000, v7
	v_mul_f32_e32 v0, 0xbfb8aa3b, v3
	v_exp_f32_e32 v0, v0
	v_lshl_add_u64 v[6:7], s[6:7], 0, v[12:13]
	v_lshl_add_u64 v[6:7], v[6:7], 0, v[160:161]
	v_mov_b32_e32 v12, v69
	v_add_f32_e32 v0, 1.0, v0
	v_rcp_f32_e32 v65, v0
	v_mul_f32_e32 v0, v10, v11
	v_cvt_pk_bf16_f32 v8, v8, v0
	v_mul_f32_e32 v0, v14, v15
	v_pk_mul_f32 v[10:11], v[64:65], v[2:3]
	v_mov_b32_e32 v14, v70
	v_mul_f32_e32 v3, v10, v11
	v_cvt_pk_bf16_f32 v9, v0, v3
	global_store_dwordx2 v[6:7], v[8:9], off
	v_mov_b32_e32 v10, v68
	s_waitcnt vmcnt(15)
	v_mov_b64_e32 v[8:9], v[82:83]
	v_lshlrev_b32_e32 v3, 16, v8
	v_mul_f32_e32 v0, 0xbfb8aa3b, v3
	v_exp_f32_e32 v0, v0
	s_nop 0
	v_add_f32_e32 v0, 1.0, v0
	v_rcp_f32_e32 v11, v0
	s_nop 0
	v_pk_mul_f32 v[10:11], v[10:11], v[2:3]
	v_and_b32_e32 v3, 0xffff0000, v8
	v_mul_f32_e32 v0, 0xbfb8aa3b, v3
	v_exp_f32_e32 v0, v0
	v_mov_b32_e32 v8, v71
	v_mul_f32_e32 v10, v10, v11
	v_add_f32_e32 v0, 1.0, v0
	v_rcp_f32_e32 v13, v0
	s_nop 0
	v_pk_mul_f32 v[12:13], v[12:13], v[2:3]
	v_lshlrev_b32_e32 v3, 16, v9
	v_mul_f32_e32 v0, 0xbfb8aa3b, v3
	v_exp_f32_e32 v0, v0
	s_nop 0
	v_add_f32_e32 v0, 1.0, v0
	v_rcp_f32_e32 v15, v0
	s_nop 0
	v_pk_mul_f32 v[14:15], v[14:15], v[2:3]
	v_and_b32_e32 v3, 0xffff0000, v9
	v_mul_f32_e32 v0, 0xbfb8aa3b, v3
	v_exp_f32_e32 v0, v0
	s_nop 0
	v_add_f32_e32 v0, 1.0, v0
	v_rcp_f32_e32 v9, v0
	v_mul_f32_e32 v0, v12, v13
	v_cvt_pk_bf16_f32 v10, v10, v0
	v_mul_f32_e32 v0, v14, v15
	v_pk_mul_f32 v[8:9], v[8:9], v[2:3]
	v_mov_b32_e32 v12, v73
	v_mul_f32_e32 v3, v8, v9
	v_cvt_pk_bf16_f32 v11, v0, v3
	global_store_dwordx2 v[6:7], v[10:11], off offset:16
	v_mov_b32_e32 v10, v72
	v_mov_b32_e32 v14, v74
	s_waitcnt vmcnt(15)
	v_mov_b64_e32 v[8:9], v[84:85]
	v_lshlrev_b32_e32 v3, 16, v8
	v_mul_f32_e32 v0, 0xbfb8aa3b, v3
	v_exp_f32_e32 v0, v0
	s_nop 0
	v_add_f32_e32 v0, 1.0, v0
	v_rcp_f32_e32 v11, v0
	s_nop 0
	v_pk_mul_f32 v[10:11], v[10:11], v[2:3]
	v_and_b32_e32 v3, 0xffff0000, v8
	v_mul_f32_e32 v0, 0xbfb8aa3b, v3
	v_exp_f32_e32 v0, v0
	v_mov_b32_e32 v8, v75
	v_mul_f32_e32 v10, v10, v11
	v_add_f32_e32 v0, 1.0, v0
	v_rcp_f32_e32 v13, v0
	s_nop 0
	v_pk_mul_f32 v[12:13], v[12:13], v[2:3]
	v_lshlrev_b32_e32 v3, 16, v9
	v_mul_f32_e32 v0, 0xbfb8aa3b, v3
	v_exp_f32_e32 v0, v0
	s_nop 0
	v_add_f32_e32 v0, 1.0, v0
	v_rcp_f32_e32 v15, v0
	s_nop 0
	v_pk_mul_f32 v[14:15], v[14:15], v[2:3]
	v_and_b32_e32 v3, 0xffff0000, v9
	v_mul_f32_e32 v0, 0xbfb8aa3b, v3
	v_exp_f32_e32 v0, v0
	s_nop 0
	v_add_f32_e32 v0, 1.0, v0
	v_rcp_f32_e32 v9, v0
	v_mul_f32_e32 v0, v12, v13
	v_cvt_pk_bf16_f32 v10, v10, v0
	v_mul_f32_e32 v0, v14, v15
	v_pk_mul_f32 v[8:9], v[8:9], v[2:3]
	v_mov_b32_e32 v12, v77
	v_mul_f32_e32 v3, v8, v9
	v_cvt_pk_bf16_f32 v11, v0, v3
	global_store_dwordx2 v[6:7], v[10:11], off offset:32
	v_mov_b32_e32 v10, v76
	v_mov_b32_e32 v14, v78
	s_waitcnt vmcnt(15)
; DI float bflo(unsigned w) { return __uint_as_float(w << 16); }
; DI float bfhi(unsigned w) { return __uint_as_float(w & 0xffff0000u); }
; DI unsigned cvt_pk_bf16(float lo, float hi) { unsigned r; asm volatile("v_cvt_pk_bf16_f32 %0, %1, %2" : "=v"(r) : "v"(lo), "v"(hi)); return r; }
; DI float siluf_(float v) { return v * __builtin_amdgcn_rcpf(1.0f + __expf(-v)); }
; DI void attn_item(const Params& p, int it, unsigned char* lds) {
;     ...
;         for (int c = 0; c < 4; ++c)
; #pragma unroll
;             for (int i4 = 0; i4 < 4; ++i4) { const int dv = 32 * c + 8 * i4 + 4 * hh;
;                 const u32x2 zz = *(const u32x2*)(P + zo + dv);
;                 const float o0 = oa[c][4 * i4 + 0] * inv * siluf_(bflo(zz.x)), o1 = oa[c][4 * i4 + 1] * inv * siluf_(bfhi(zz.x));
;                 const float o2 = oa[c][4 * i4 + 2] * inv * siluf_(bflo(zz.y)), o3 = oa[c][4 * i4 + 3] * inv * siluf_(bfhi(zz.y));
;                 u32x2 wv; wv.x = cvt_pk_bf16(o0, o1); wv.y = cvt_pk_bf16(o2, o3);
;                 *(u32x2*)(YA + yo + dv) = wv; }
	v_mov_b64_e32 v[8:9], v[86:87]
	v_lshlrev_b32_e32 v3, 16, v8
	v_mul_f32_e32 v0, 0xbfb8aa3b, v3
	v_exp_f32_e32 v0, v0
	s_nop 0
	v_add_f32_e32 v0, 1.0, v0
	v_rcp_f32_e32 v11, v0
	s_nop 0
	v_pk_mul_f32 v[10:11], v[10:11], v[2:3]
	v_and_b32_e32 v3, 0xffff0000, v8
	v_mul_f32_e32 v0, 0xbfb8aa3b, v3
	v_exp_f32_e32 v0, v0
	v_mov_b32_e32 v8, v79
	v_mul_f32_e32 v10, v10, v11
	v_add_f32_e32 v0, 1.0, v0
	v_rcp_f32_e32 v13, v0
	s_nop 0
	v_pk_mul_f32 v[12:13], v[12:13], v[2:3]
	v_lshlrev_b32_e32 v3, 16, v9
	v_mul_f32_e32 v0, 0xbfb8aa3b, v3
	v_exp_f32_e32 v0, v0
	s_nop 0
	v_add_f32_e32 v0, 1.0, v0
	v_rcp_f32_e32 v15, v0
	s_nop 0
	v_pk_mul_f32 v[14:15], v[14:15], v[2:3]
	v_and_b32_e32 v3, 0xffff0000, v9
	v_mul_f32_e32 v0, 0xbfb8aa3b, v3
	v_exp_f32_e32 v0, v0
	s_nop 0
	v_add_f32_e32 v0, 1.0, v0
	v_rcp_f32_e32 v9, v0
	v_mul_f32_e32 v0, v12, v13
	v_cvt_pk_bf16_f32 v10, v10, v0
	v_mul_f32_e32 v0, v14, v15
	v_pk_mul_f32 v[8:9], v[8:9], v[2:3]
	v_mov_b32_e32 v12, v49
	v_mul_f32_e32 v3, v8, v9
	v_cvt_pk_bf16_f32 v11, v0, v3
	global_store_dwordx2 v[6:7], v[10:11], off offset:48
	v_mov_b32_e32 v10, v48
	v_mov_b32_e32 v14, v50
	s_waitcnt vmcnt(15)
	v_mov_b64_e32 v[8:9], v[88:89]
	v_lshlrev_b32_e32 v3, 16, v8
	v_mul_f32_e32 v0, 0xbfb8aa3b, v3
	v_exp_f32_e32 v0, v0
	s_nop 0
	v_add_f32_e32 v0, 1.0, v0
	v_rcp_f32_e32 v11, v0
	s_nop 0
	v_pk_mul_f32 v[10:11], v[10:11], v[2:3]
	v_and_b32_e32 v3, 0xffff0000, v8
	v_mul_f32_e32 v0, 0xbfb8aa3b, v3
	v_exp_f32_e32 v0, v0
	v_mov_b32_e32 v8, v51
	v_mul_f32_e32 v10, v10, v11
	v_add_f32_e32 v0, 1.0, v0
	v_rcp_f32_e32 v13, v0
	s_nop 0
	v_pk_mul_f32 v[12:13], v[12:13], v[2:3]
	v_lshlrev_b32_e32 v3, 16, v9
	v_mul_f32_e32 v0, 0xbfb8aa3b, v3
	v_exp_f32_e32 v0, v0
	s_nop 0
	v_add_f32_e32 v0, 1.0, v0
	v_rcp_f32_e32 v15, v0
	s_nop 0
	v_pk_mul_f32 v[14:15], v[14:15], v[2:3]
	v_and_b32_e32 v3, 0xffff0000, v9
	v_mul_f32_e32 v0, 0xbfb8aa3b, v3
	v_exp_f32_e32 v0, v0
	s_nop 0
	v_add_f32_e32 v0, 1.0, v0
	v_rcp_f32_e32 v9, v0
	v_mul_f32_e32 v0, v12, v13
	v_cvt_pk_bf16_f32 v10, v10, v0
	v_mul_f32_e32 v0, v14, v15
	v_pk_mul_f32 v[8:9], v[8:9], v[2:3]
	v_mov_b32_e32 v12, v53
	v_mul_f32_e32 v3, v8, v9
	v_cvt_pk_bf16_f32 v11, v0, v3
	global_store_dwordx2 v[6:7], v[10:11], off offset:64
	v_mov_b32_e32 v10, v52
	v_mov_b32_e32 v14, v54
	s_waitcnt vmcnt(15)
	v_mov_b64_e32 v[8:9], v[90:91]
	v_lshlrev_b32_e32 v3, 16, v8
	v_mul_f32_e32 v0, 0xbfb8aa3b, v3
	v_exp_f32_e32 v0, v0
	s_nop 0
	v_add_f32_e32 v0, 1.0, v0
	v_rcp_f32_e32 v11, v0
	s_nop 0
	v_pk_mul_f32 v[10:11], v[10:11], v[2:3]
	v_and_b32_e32 v3, 0xffff0000, v8
	v_mul_f32_e32 v0, 0xbfb8aa3b, v3
	v_exp_f32_e32 v0, v0
	v_mov_b32_e32 v8, v55
	v_mul_f32_e32 v10, v10, v11
	v_add_f32_e32 v0, 1.0, v0
	v_rcp_f32_e32 v13, v0
	s_nop 0
	v_pk_mul_f32 v[12:13], v[12:13], v[2:3]
	v_lshlrev_b32_e32 v3, 16, v9
	v_mul_f32_e32 v0, 0xbfb8aa3b, v3
	v_exp_f32_e32 v0, v0
	s_nop 0
	v_add_f32_e32 v0, 1.0, v0
	v_rcp_f32_e32 v15, v0
	s_nop 0
	v_pk_mul_f32 v[14:15], v[14:15], v[2:3]
	v_and_b32_e32 v3, 0xffff0000, v9
	v_mul_f32_e32 v0, 0xbfb8aa3b, v3
	v_exp_f32_e32 v0, v0
	s_nop 0
	v_add_f32_e32 v0, 1.0, v0
	v_rcp_f32_e32 v9, v0
	v_mul_f32_e32 v0, v12, v13
	v_cvt_pk_bf16_f32 v10, v10, v0
	v_mul_f32_e32 v0, v14, v15
	v_pk_mul_f32 v[8:9], v[8:9], v[2:3]
	v_mov_b32_e32 v12, v57
	v_mul_f32_e32 v3, v8, v9
	v_cvt_pk_bf16_f32 v11, v0, v3
	global_store_dwordx2 v[6:7], v[10:11], off offset:80
	v_mov_b32_e32 v10, v56
	v_mov_b32_e32 v14, v58
	s_waitcnt vmcnt(15)
	v_mov_b64_e32 v[8:9], v[92:93]
	v_lshlrev_b32_e32 v3, 16, v8
	v_mul_f32_e32 v0, 0xbfb8aa3b, v3
	v_exp_f32_e32 v0, v0
	s_nop 0
	v_add_f32_e32 v0, 1.0, v0
	v_rcp_f32_e32 v11, v0
	s_nop 0
	v_pk_mul_f32 v[10:11], v[10:11], v[2:3]
	v_and_b32_e32 v3, 0xffff0000, v8
	v_mul_f32_e32 v0, 0xbfb8aa3b, v3
	v_exp_f32_e32 v0, v0
	v_mov_b32_e32 v8, v59
	v_mul_f32_e32 v10, v10, v11
	v_add_f32_e32 v0, 1.0, v0
	v_rcp_f32_e32 v13, v0
	s_nop 0
	v_pk_mul_f32 v[12:13], v[12:13], v[2:3]
	v_lshlrev_b32_e32 v3, 16, v9
	v_mul_f32_e32 v0, 0xbfb8aa3b, v3
	v_exp_f32_e32 v0, v0
	s_nop 0
	v_add_f32_e32 v0, 1.0, v0
	v_rcp_f32_e32 v15, v0
	s_nop 0
	v_pk_mul_f32 v[14:15], v[14:15], v[2:3]
	v_and_b32_e32 v3, 0xffff0000, v9
	v_mul_f32_e32 v0, 0xbfb8aa3b, v3
	v_exp_f32_e32 v0, v0
	s_nop 0
	v_add_f32_e32 v0, 1.0, v0
	v_rcp_f32_e32 v9, v0
	v_mul_f32_e32 v0, v12, v13
	v_cvt_pk_bf16_f32 v10, v10, v0
	v_mul_f32_e32 v0, v14, v15
	v_pk_mul_f32 v[8:9], v[8:9], v[2:3]
	v_mov_b32_e32 v12, v61
	v_mul_f32_e32 v3, v8, v9
	v_cvt_pk_bf16_f32 v11, v0, v3
	global_store_dwordx2 v[6:7], v[10:11], off offset:96
	v_mov_b32_e32 v10, v60
	v_mov_b32_e32 v14, v62
	s_waitcnt vmcnt(15)
	v_mov_b64_e32 v[8:9], v[94:95]
	v_lshlrev_b32_e32 v3, 16, v8
	v_mul_f32_e32 v0, 0xbfb8aa3b, v3
	v_exp_f32_e32 v0, v0
	s_nop 0
	v_add_f32_e32 v0, 1.0, v0
	v_rcp_f32_e32 v11, v0
	s_nop 0
	v_pk_mul_f32 v[10:11], v[10:11], v[2:3]
	v_and_b32_e32 v3, 0xffff0000, v8
	v_mul_f32_e32 v0, 0xbfb8aa3b, v3
	v_exp_f32_e32 v0, v0
	v_mov_b32_e32 v8, v63
	v_mul_f32_e32 v10, v10, v11
	v_add_f32_e32 v0, 1.0, v0
	v_rcp_f32_e32 v13, v0
	s_nop 0
	v_pk_mul_f32 v[12:13], v[12:13], v[2:3]
	v_lshlrev_b32_e32 v3, 16, v9
	v_mul_f32_e32 v0, 0xbfb8aa3b, v3
	v_exp_f32_e32 v0, v0
	s_nop 0
	v_add_f32_e32 v0, 1.0, v0
	v_rcp_f32_e32 v15, v0
	s_nop 0
	v_pk_mul_f32 v[14:15], v[14:15], v[2:3]
	v_and_b32_e32 v3, 0xffff0000, v9
	v_mul_f32_e32 v0, 0xbfb8aa3b, v3
	v_exp_f32_e32 v0, v0
	s_nop 0
	v_add_f32_e32 v0, 1.0, v0
	v_rcp_f32_e32 v9, v0
	v_mul_f32_e32 v0, v12, v13
	v_cvt_pk_bf16_f32 v10, v10, v0
	v_mul_f32_e32 v0, v14, v15
	v_pk_mul_f32 v[8:9], v[8:9], v[2:3]
	v_mov_b32_e32 v12, v33
	v_mul_f32_e32 v3, v8, v9
	v_cvt_pk_bf16_f32 v11, v0, v3
	global_store_dwordx2 v[6:7], v[10:11], off offset:112
	v_mov_b32_e32 v10, v32
	v_mov_b32_e32 v14, v34
	s_waitcnt vmcnt(15)
; DI float bflo(unsigned w) { return __uint_as_float(w << 16); }
; DI float bfhi(unsigned w) { return __uint_as_float(w & 0xffff0000u); }
; DI unsigned cvt_pk_bf16(float lo, float hi) { unsigned r; asm volatile("v_cvt_pk_bf16_f32 %0, %1, %2" : "=v"(r) : "v"(lo), "v"(hi)); return r; }
; DI float siluf_(float v) { return v * __builtin_amdgcn_rcpf(1.0f + __expf(-v)); }
; DI void attn_item(const Params& p, int it, unsigned char* lds) {
;     ...
;         for (int c = 0; c < 4; ++c)
; #pragma unroll
;             for (int i4 = 0; i4 < 4; ++i4) { const int dv = 32 * c + 8 * i4 + 4 * hh;
;                 const u32x2 zz = *(const u32x2*)(P + zo + dv);
;                 const float o0 = oa[c][4 * i4 + 0] * inv * siluf_(bflo(zz.x)), o1 = oa[c][4 * i4 + 1] * inv * siluf_(bfhi(zz.x));
;                 const float o2 = oa[c][4 * i4 + 2] * inv * siluf_(bflo(zz.y)), o3 = oa[c][4 * i4 + 3] * inv * siluf_(bfhi(zz.y));
;                 u32x2 wv; wv.x = cvt_pk_bf16(o0, o1); wv.y = cvt_pk_bf16(o2, o3);
;                 *(u32x2*)(YA + yo + dv) = wv; }
	v_mov_b64_e32 v[8:9], v[96:97]
	v_lshlrev_b32_e32 v3, 16, v8
	v_mul_f32_e32 v0, 0xbfb8aa3b, v3
	v_exp_f32_e32 v0, v0
	s_nop 0
	v_add_f32_e32 v0, 1.0, v0
	v_rcp_f32_e32 v11, v0
	s_nop 0
	v_pk_mul_f32 v[10:11], v[10:11], v[2:3]
	v_and_b32_e32 v3, 0xffff0000, v8
	v_mul_f32_e32 v0, 0xbfb8aa3b, v3
	v_exp_f32_e32 v0, v0
	v_mov_b32_e32 v8, v35
	v_mul_f32_e32 v10, v10, v11
	v_add_f32_e32 v0, 1.0, v0
	v_rcp_f32_e32 v13, v0
	s_nop 0
	v_pk_mul_f32 v[12:13], v[12:13], v[2:3]
	v_lshlrev_b32_e32 v3, 16, v9
	v_mul_f32_e32 v0, 0xbfb8aa3b, v3
	v_exp_f32_e32 v0, v0
	s_nop 0
	v_add_f32_e32 v0, 1.0, v0
	v_rcp_f32_e32 v15, v0
	s_nop 0
	v_pk_mul_f32 v[14:15], v[14:15], v[2:3]
	v_and_b32_e32 v3, 0xffff0000, v9
	v_mul_f32_e32 v0, 0xbfb8aa3b, v3
	v_exp_f32_e32 v0, v0
	s_nop 0
	v_add_f32_e32 v0, 1.0, v0
	v_rcp_f32_e32 v9, v0
	v_mul_f32_e32 v0, v12, v13
	v_cvt_pk_bf16_f32 v10, v10, v0
	v_mul_f32_e32 v0, v14, v15
	v_pk_mul_f32 v[8:9], v[8:9], v[2:3]
	v_mov_b32_e32 v12, v37
	v_mul_f32_e32 v3, v8, v9
	v_cvt_pk_bf16_f32 v11, v0, v3
	global_store_dwordx2 v[6:7], v[10:11], off offset:128
	v_mov_b32_e32 v10, v36
	v_mov_b32_e32 v14, v38
	s_waitcnt vmcnt(15)
	v_mov_b64_e32 v[8:9], v[98:99]
	v_lshlrev_b32_e32 v3, 16, v8
	v_mul_f32_e32 v0, 0xbfb8aa3b, v3
	v_exp_f32_e32 v0, v0
	s_nop 0
	v_add_f32_e32 v0, 1.0, v0
	v_rcp_f32_e32 v11, v0
	s_nop 0
	v_pk_mul_f32 v[10:11], v[10:11], v[2:3]
	v_and_b32_e32 v3, 0xffff0000, v8
	v_mul_f32_e32 v0, 0xbfb8aa3b, v3
	v_exp_f32_e32 v0, v0
	v_mov_b32_e32 v8, v39
	v_mul_f32_e32 v10, v10, v11
	v_add_f32_e32 v0, 1.0, v0
	v_rcp_f32_e32 v13, v0
	s_nop 0
	v_pk_mul_f32 v[12:13], v[12:13], v[2:3]
	v_lshlrev_b32_e32 v3, 16, v9
	v_mul_f32_e32 v0, 0xbfb8aa3b, v3
	v_exp_f32_e32 v0, v0
	s_nop 0
	v_add_f32_e32 v0, 1.0, v0
	v_rcp_f32_e32 v15, v0
	s_nop 0
	v_pk_mul_f32 v[14:15], v[14:15], v[2:3]
	v_and_b32_e32 v3, 0xffff0000, v9
	v_mul_f32_e32 v0, 0xbfb8aa3b, v3
	v_exp_f32_e32 v0, v0
	s_nop 0
	v_add_f32_e32 v0, 1.0, v0
	v_rcp_f32_e32 v9, v0
	v_mul_f32_e32 v0, v12, v13
	v_cvt_pk_bf16_f32 v10, v10, v0
	v_mul_f32_e32 v0, v14, v15
	v_pk_mul_f32 v[8:9], v[8:9], v[2:3]
	v_mov_b32_e32 v12, v41
	v_mul_f32_e32 v3, v8, v9
	v_cvt_pk_bf16_f32 v11, v0, v3
	global_store_dwordx2 v[6:7], v[10:11], off offset:144
	v_mov_b32_e32 v10, v40
	v_mov_b32_e32 v14, v42
	s_waitcnt vmcnt(15)
	v_mov_b64_e32 v[8:9], v[100:101]
	v_lshlrev_b32_e32 v3, 16, v8
	v_mul_f32_e32 v0, 0xbfb8aa3b, v3
	v_exp_f32_e32 v0, v0
	s_nop 0
	v_add_f32_e32 v0, 1.0, v0
	v_rcp_f32_e32 v11, v0
	s_nop 0
	v_pk_mul_f32 v[10:11], v[10:11], v[2:3]
	v_and_b32_e32 v3, 0xffff0000, v8
	v_mul_f32_e32 v0, 0xbfb8aa3b, v3
	v_exp_f32_e32 v0, v0
	v_mov_b32_e32 v8, v43
	v_mul_f32_e32 v10, v10, v11
	v_add_f32_e32 v0, 1.0, v0
	v_rcp_f32_e32 v13, v0
	s_nop 0
	v_pk_mul_f32 v[12:13], v[12:13], v[2:3]
	v_lshlrev_b32_e32 v3, 16, v9
	v_mul_f32_e32 v0, 0xbfb8aa3b, v3
	v_exp_f32_e32 v0, v0
	s_nop 0
	v_add_f32_e32 v0, 1.0, v0
	v_rcp_f32_e32 v15, v0
	s_nop 0
	v_pk_mul_f32 v[14:15], v[14:15], v[2:3]
	v_and_b32_e32 v3, 0xffff0000, v9
	v_mul_f32_e32 v0, 0xbfb8aa3b, v3
	v_exp_f32_e32 v0, v0
	s_nop 0
	v_add_f32_e32 v0, 1.0, v0
	v_rcp_f32_e32 v9, v0
	v_mul_f32_e32 v0, v12, v13
	v_cvt_pk_bf16_f32 v10, v10, v0
	v_mul_f32_e32 v0, v14, v15
	v_pk_mul_f32 v[8:9], v[8:9], v[2:3]
	v_mov_b32_e32 v12, v45
	v_mul_f32_e32 v3, v8, v9
	v_cvt_pk_bf16_f32 v11, v0, v3
	global_store_dwordx2 v[6:7], v[10:11], off offset:160
	v_mov_b32_e32 v10, v44
	v_mov_b32_e32 v14, v46
	s_waitcnt vmcnt(15)
	v_mov_b64_e32 v[8:9], v[102:103]
	v_lshlrev_b32_e32 v3, 16, v8
	v_mul_f32_e32 v0, 0xbfb8aa3b, v3
	v_exp_f32_e32 v0, v0
	s_nop 0
	v_add_f32_e32 v0, 1.0, v0
	v_rcp_f32_e32 v11, v0
	s_nop 0
	v_pk_mul_f32 v[10:11], v[10:11], v[2:3]
	v_and_b32_e32 v3, 0xffff0000, v8
	v_mul_f32_e32 v0, 0xbfb8aa3b, v3
	v_exp_f32_e32 v0, v0
	v_mov_b32_e32 v8, v47
	v_mul_f32_e32 v10, v10, v11
	v_add_f32_e32 v0, 1.0, v0
	v_rcp_f32_e32 v13, v0
	s_nop 0
	v_pk_mul_f32 v[12:13], v[12:13], v[2:3]
	v_lshlrev_b32_e32 v3, 16, v9
	v_mul_f32_e32 v0, 0xbfb8aa3b, v3
	v_exp_f32_e32 v0, v0
	s_nop 0
	v_add_f32_e32 v0, 1.0, v0
	v_rcp_f32_e32 v15, v0
	s_nop 0
	v_pk_mul_f32 v[14:15], v[14:15], v[2:3]
	v_and_b32_e32 v3, 0xffff0000, v9
	v_mul_f32_e32 v0, 0xbfb8aa3b, v3
	v_exp_f32_e32 v0, v0
	s_nop 0
	v_add_f32_e32 v0, 1.0, v0
	v_rcp_f32_e32 v9, v0
	v_mul_f32_e32 v0, v12, v13
	v_cvt_pk_bf16_f32 v10, v10, v0
	v_mul_f32_e32 v0, v14, v15
	v_pk_mul_f32 v[8:9], v[8:9], v[2:3]
	v_mov_b32_e32 v12, v17
	v_mul_f32_e32 v3, v8, v9
	v_cvt_pk_bf16_f32 v11, v0, v3
	global_store_dwordx2 v[6:7], v[10:11], off offset:176
	v_mov_b32_e32 v10, v16
	v_mov_b32_e32 v14, v18
	s_waitcnt vmcnt(15)
; DI float bflo(unsigned w) { return __uint_as_float(w << 16); }
; DI float bfhi(unsigned w) { return __uint_as_float(w & 0xffff0000u); }
; DI unsigned cvt_pk_bf16(float lo, float hi) { unsigned r; asm volatile("v_cvt_pk_bf16_f32 %0, %1, %2" : "=v"(r) : "v"(lo), "v"(hi)); return r; }
; DI float siluf_(float v) { return v * __builtin_amdgcn_rcpf(1.0f + __expf(-v)); }
; DI void attn_item(const Params& p, int it, unsigned char* lds) {
;     ...
;         for (int c = 0; c < 4; ++c)
; #pragma unroll
;             for (int i4 = 0; i4 < 4; ++i4) { const int dv = 32 * c + 8 * i4 + 4 * hh;
;                 const u32x2 zz = *(const u32x2*)(P + zo + dv);
;                 const float o0 = oa[c][4 * i4 + 0] * inv * siluf_(bflo(zz.x)), o1 = oa[c][4 * i4 + 1] * inv * siluf_(bfhi(zz.x));
;                 const float o2 = oa[c][4 * i4 + 2] * inv * siluf_(bflo(zz.y)), o3 = oa[c][4 * i4 + 3] * inv * siluf_(bfhi(zz.y));
;                 u32x2 wv; wv.x = cvt_pk_bf16(o0, o1); wv.y = cvt_pk_bf16(o2, o3);
;                 *(u32x2*)(YA + yo + dv) = wv; }
; __global__ void __launch_bounds__(NTHREADS, 2) fwd_megakernel(Params p) {
;     ...
;         for (int it = cx; it < 1024; it += gridDim.x) attn_item(p, it, lds);
	v_mov_b64_e32 v[8:9], v[104:105]
	v_lshlrev_b32_e32 v3, 16, v8
	v_mul_f32_e32 v0, 0xbfb8aa3b, v3
	v_exp_f32_e32 v0, v0
	s_nop 0
	v_add_f32_e32 v0, 1.0, v0
	v_rcp_f32_e32 v11, v0
	s_nop 0
	v_pk_mul_f32 v[10:11], v[10:11], v[2:3]
	v_and_b32_e32 v3, 0xffff0000, v8
	v_mul_f32_e32 v0, 0xbfb8aa3b, v3
	v_exp_f32_e32 v0, v0
	v_mov_b32_e32 v8, v19
	v_mul_f32_e32 v10, v10, v11
	v_add_f32_e32 v0, 1.0, v0
	v_rcp_f32_e32 v13, v0
	s_nop 0
	v_pk_mul_f32 v[12:13], v[12:13], v[2:3]
	v_lshlrev_b32_e32 v3, 16, v9
	v_mul_f32_e32 v0, 0xbfb8aa3b, v3
	v_exp_f32_e32 v0, v0
	s_nop 0
	v_add_f32_e32 v0, 1.0, v0
	v_rcp_f32_e32 v15, v0
	s_nop 0
	v_pk_mul_f32 v[14:15], v[14:15], v[2:3]
	v_and_b32_e32 v3, 0xffff0000, v9
	v_mul_f32_e32 v0, 0xbfb8aa3b, v3
	v_exp_f32_e32 v0, v0
	s_nop 0
	v_add_f32_e32 v0, 1.0, v0
	v_rcp_f32_e32 v9, v0
	v_mul_f32_e32 v0, v12, v13
	v_cvt_pk_bf16_f32 v10, v10, v0
	v_mul_f32_e32 v0, v14, v15
	v_pk_mul_f32 v[8:9], v[8:9], v[2:3]
	v_mov_b32_e32 v12, v21
	v_mul_f32_e32 v3, v8, v9
	v_cvt_pk_bf16_f32 v11, v0, v3
	global_store_dwordx2 v[6:7], v[10:11], off offset:192
	v_mov_b32_e32 v10, v20
	v_mov_b32_e32 v14, v22
	s_waitcnt vmcnt(15)
	v_mov_b64_e32 v[8:9], v[106:107]
	v_lshlrev_b32_e32 v3, 16, v8
	v_mul_f32_e32 v0, 0xbfb8aa3b, v3
	v_exp_f32_e32 v0, v0
	s_nop 0
	v_add_f32_e32 v0, 1.0, v0
	v_rcp_f32_e32 v11, v0
	s_nop 0
	v_pk_mul_f32 v[10:11], v[10:11], v[2:3]
	v_and_b32_e32 v3, 0xffff0000, v8
	v_mul_f32_e32 v0, 0xbfb8aa3b, v3
	v_exp_f32_e32 v0, v0
	v_mov_b32_e32 v8, v23
	v_mul_f32_e32 v10, v10, v11
	v_add_f32_e32 v0, 1.0, v0
	v_rcp_f32_e32 v13, v0
	s_nop 0
	v_pk_mul_f32 v[12:13], v[12:13], v[2:3]
	v_lshlrev_b32_e32 v3, 16, v9
	v_mul_f32_e32 v0, 0xbfb8aa3b, v3
	v_exp_f32_e32 v0, v0
	s_nop 0
	v_add_f32_e32 v0, 1.0, v0
	v_rcp_f32_e32 v15, v0
	s_nop 0
	v_pk_mul_f32 v[14:15], v[14:15], v[2:3]
	v_and_b32_e32 v3, 0xffff0000, v9
	v_mul_f32_e32 v0, 0xbfb8aa3b, v3
	v_exp_f32_e32 v0, v0
	s_nop 0
	v_add_f32_e32 v0, 1.0, v0
	v_rcp_f32_e32 v9, v0
	v_mul_f32_e32 v0, v12, v13
	v_cvt_pk_bf16_f32 v10, v10, v0
	v_mul_f32_e32 v0, v14, v15
	v_pk_mul_f32 v[8:9], v[8:9], v[2:3]
	v_mov_b32_e32 v12, v25
	v_mul_f32_e32 v3, v8, v9
	v_cvt_pk_bf16_f32 v11, v0, v3
	global_store_dwordx2 v[6:7], v[10:11], off offset:208
	v_mov_b32_e32 v10, v24
	v_mov_b32_e32 v14, v26
	s_waitcnt vmcnt(15)
	v_mov_b64_e32 v[8:9], v[108:109]
	v_lshlrev_b32_e32 v3, 16, v8
	v_mul_f32_e32 v0, 0xbfb8aa3b, v3
	v_exp_f32_e32 v0, v0
	s_nop 0
	v_add_f32_e32 v0, 1.0, v0
	v_rcp_f32_e32 v11, v0
	s_nop 0
	v_pk_mul_f32 v[10:11], v[10:11], v[2:3]
	v_and_b32_e32 v3, 0xffff0000, v8
	v_mul_f32_e32 v0, 0xbfb8aa3b, v3
	v_exp_f32_e32 v0, v0
	v_mov_b32_e32 v8, v27
	v_mul_f32_e32 v10, v10, v11
	v_add_f32_e32 v0, 1.0, v0
	v_rcp_f32_e32 v13, v0
	s_nop 0
	v_pk_mul_f32 v[12:13], v[12:13], v[2:3]
	v_lshlrev_b32_e32 v3, 16, v9
	v_mul_f32_e32 v0, 0xbfb8aa3b, v3
	v_exp_f32_e32 v0, v0
	s_nop 0
	v_add_f32_e32 v0, 1.0, v0
	v_rcp_f32_e32 v15, v0
	s_nop 0
	v_pk_mul_f32 v[14:15], v[14:15], v[2:3]
	v_and_b32_e32 v3, 0xffff0000, v9
	v_mul_f32_e32 v0, 0xbfb8aa3b, v3
	v_exp_f32_e32 v0, v0
	s_nop 0
	v_add_f32_e32 v0, 1.0, v0
	v_rcp_f32_e32 v9, v0
	v_mul_f32_e32 v0, v12, v13
	v_cvt_pk_bf16_f32 v10, v10, v0
	v_mul_f32_e32 v0, v14, v15
	v_pk_mul_f32 v[8:9], v[8:9], v[2:3]
	v_mov_b32_e32 v12, v30
	v_mul_f32_e32 v3, v8, v9
	v_cvt_pk_bf16_f32 v11, v0, v3
	global_store_dwordx2 v[6:7], v[10:11], off offset:224
	v_mov_b32_e32 v8, v28
	v_mov_b32_e32 v10, v29
	s_waitcnt vmcnt(15)
	v_mov_b64_e32 v[4:5], v[110:111]
	v_lshlrev_b32_e32 v3, 16, v4
	v_mul_f32_e32 v0, 0xbfb8aa3b, v3
	v_exp_f32_e32 v0, v0
	s_nop 0
	v_add_f32_e32 v0, 1.0, v0
	v_rcp_f32_e32 v9, v0
	s_nop 0
	v_pk_mul_f32 v[8:9], v[8:9], v[2:3]
	v_and_b32_e32 v3, 0xffff0000, v4
	v_mul_f32_e32 v0, 0xbfb8aa3b, v3
	v_exp_f32_e32 v0, v0
	v_mov_b32_e32 v4, v31
	v_mul_f32_e32 v8, v8, v9
	v_add_f32_e32 v0, 1.0, v0
	v_rcp_f32_e32 v11, v0
	s_nop 0
	v_pk_mul_f32 v[10:11], v[10:11], v[2:3]
	v_lshlrev_b32_e32 v3, 16, v5
	v_mul_f32_e32 v0, 0xbfb8aa3b, v3
	v_exp_f32_e32 v0, v0
	s_nop 0
	v_add_f32_e32 v0, 1.0, v0
	v_rcp_f32_e32 v13, v0
	s_nop 0
	v_pk_mul_f32 v[12:13], v[12:13], v[2:3]
	v_and_b32_e32 v3, 0xffff0000, v5
	v_mul_f32_e32 v0, 0xbfb8aa3b, v3
	v_exp_f32_e32 v0, v0
	s_nop 0
	v_add_f32_e32 v0, 1.0, v0
	v_rcp_f32_e32 v5, v0
	v_mul_f32_e32 v0, v10, v11
	v_cvt_pk_bf16_f32 v8, v8, v0
	v_mul_f32_e32 v0, v12, v13
	v_pk_mul_f32 v[2:3], v[4:5], v[2:3]
	s_nop 0
	v_mul_f32_e32 v2, v2, v3
	v_cvt_pk_bf16_f32 v9, v0, v2
	global_store_dwordx2 v[6:7], v[8:9], off offset:240
	s_cbranch_scc0 .LBB0_592
